# GLA chunk epilogue: pair_tiles via v_permlane16_swap (no bpermute/cndmask) and head-norm LDS reads issued together; on top of v44
# speedup vs baseline: 1.0030x; 1.0030x over previous
; #define LAS __attribute__((address_space(3)))
; #define LDS_BARRIER() asm volatile("s_waitcnt lgkmcnt(0)\n\ts_barrier" ::: "memory")
; __device__ __forceinline__ void gla_phase(LAS unsigned char* lds, const bf16_t* P, const float* hn, bf16_t* O, int G, int wg) {
;     ...
;             for (int i = 0; i < 8; ++i) { q0[i] = bf2f(rq[i]); q1[i] = bf2f(rq[i] >> 16); l0[i] = bf2f(rl[i]) * LOG2E; l1[i] = bf2f(rl[i] >> 16) * LOG2E; run0 += l0[i]; b0[i] = run0; run1 += l1[i]; b1[i] = run1; }
; #pragma unroll
;             for (int i = 0; i < 4; ++i) { vt0[i] = (rv[2 * i] & 0xffffu) | (rv[2 * i + 1] << 16); vt1[i] = (rv[2 * i] >> 16) | (rv[2 * i + 1] & 0xffff0000u); }
;             { const int cn = (c < 31) ? c + 1 : 31;
;               const bf16_t* pp = pbase + (size_t)(cn * 64 + tq * 8) * 4096;
; #pragma unroll
;                 for (int i = 0; i < 8; ++i) { rq[i] = *(const unsigned*)(pp + (size_t)i * 4096); rl[i] = *(const unsigned*)(pp + (size_t)i * 4096 + 1024); rv[i] = *(const unsigned*)(pp + (size_t)i * 4096 + 2048); } }
;             *(LAS f32x2*)(lds + PART + (tq * 128 + 2 * dp) * 4) = (f32x2){run0, run1};
;             LDS_BARRIER();
;             if (c > 0) GLA_EPILOGUE(c - 1);
.LBB0_1402:
	s_add_i32 s94, s95, 64
	s_cmpk_eq_i32 s95, 0x7c0
	s_cselect_b32 s16, s95, s94
	v_add_u32_e32 v16, s16, v82
	v_ashrrev_i32_e32 v17, 31, v16
	v_lshlrev_b64 v[16:17], 13, v[16:17]
	v_lshl_add_u64 v[16:17], v[102:103], 0, v[16:17]
	v_add_co_u32_e32 v18, vcc, s23, v16
	s_waitcnt vmcnt(20)
	v_lshlrev_b32_e32 v40, 16, v93
	v_addc_co_u32_e32 v19, vcc, 0, v17, vcc
	v_add_co_u32_e32 v20, vcc, s31, v16
	v_and_b32_e32 v41, 0xffff0000, v93
	s_nop 0
	v_addc_co_u32_e32 v21, vcc, 0, v17, vcc
	v_add_co_u32_e32 v22, vcc, s33, v16
	s_waitcnt vmcnt(17)
	v_lshlrev_b32_e32 v42, 16, v97
	v_addc_co_u32_e32 v23, vcc, 0, v17, vcc
	v_add_co_u32_e32 v24, vcc, s19, v16
	v_and_b32_e32 v43, 0xffff0000, v97
	s_nop 0
	v_addc_co_u32_e32 v25, vcc, 0, v17, vcc
	v_add_co_u32_e32 v26, vcc, s92, v16
	s_waitcnt vmcnt(14)
	v_lshlrev_b32_e32 v44, 16, v185
	v_addc_co_u32_e32 v27, vcc, 0, v17, vcc
	v_and_b32_e32 v45, 0xffff0000, v185
	global_load_dword v191, v[22:23], off
	global_load_dword v93, v[22:23], off offset:2048
	global_load_dword v194, v[24:25], off offset:-4096
	global_load_dword v192, v[24:25], off
	global_load_dword v97, v[24:25], off offset:2048
	global_load_dword v195, v[26:27], off offset:-4096
	global_load_dword v193, v[26:27], off
	global_load_dword v185, v[26:27], off offset:2048
	v_add_co_u32_e32 v24, vcc, 0xb000, v16
	s_waitcnt vmcnt(14)
	v_lshlrev_b32_e32 v34, 16, v189
	v_addc_co_u32_e32 v25, vcc, 0, v17, vcc
	v_add_co_u32_e32 v26, vcc, s12, v16
	v_and_b32_e32 v35, 0xffff0000, v189
	s_nop 0
	v_addc_co_u32_e32 v27, vcc, 0, v17, vcc
	v_add_co_u32_e32 v28, vcc, 0xd000, v16
	v_lshlrev_b32_e32 v46, 16, v187
	s_nop 0
	v_addc_co_u32_e32 v29, vcc, 0, v17, vcc
	v_add_co_u32_e32 v30, vcc, 0xe000, v16
	v_and_b32_e32 v47, 0xffff0000, v187
	s_nop 0
	v_addc_co_u32_e32 v31, vcc, 0, v17, vcc
	v_lshlrev_b32_e32 v48, 16, v188
	v_and_b32_e32 v49, 0xffff0000, v188
	global_load_dword v197, v[16:17], off
	global_load_dword v189, v[16:17], off offset:2048
	global_load_dword v199, v[24:25], off
	global_load_dword v196, v[26:27], off
	global_load_dword v187, v[26:27], off offset:2048
	global_load_dword v201, v[28:29], off
	global_load_dword v198, v[30:31], off
	global_load_dword v188, v[30:31], off offset:2048
	v_add_co_u32_e32 v16, vcc, 0xf000, v16
	s_waitcnt vmcnt(19)
	v_lshlrev_b32_e32 v36, 16, v190
	v_and_b32_e32 v37, 0xffff0000, v190
	v_lshlrev_b32_e32 v38, 16, v186
	v_and_b32_e32 v39, 0xffff0000, v186
	v_addc_co_u32_e32 v17, vcc, 0, v17, vcc
	global_load_dword v203, v[18:19], off offset:-4096
	global_load_dword v200, v[18:19], off
	global_load_dword v190, v[18:19], off offset:2048
	global_load_dword v204, v[20:21], off offset:-4096
	global_load_dword v202, v[20:21], off
	global_load_dword v186, v[20:21], off offset:2048
	global_load_dword v206, v[22:23], off offset:-4096
	global_load_dword v205, v[16:17], off
	v_pk_fma_f32 v[30:31], v[34:35], s[18:19], 0 op_sel_hi:[1,0,0]
	s_cmp_eq_u32 s95, 0
	v_pk_fma_f32 v[28:29], v[36:37], s[18:19], v[30:31] op_sel_hi:[1,0,1]
	s_mov_b32 s16, 0
	v_pk_fma_f32 v[26:27], v[38:39], s[18:19], v[28:29] op_sel_hi:[1,0,1]
	s_nop 0
	v_pk_fma_f32 v[24:25], v[40:41], s[18:19], v[26:27] op_sel_hi:[1,0,1]
	s_nop 0
	v_pk_fma_f32 v[22:23], v[42:43], s[18:19], v[24:25] op_sel_hi:[1,0,1]
	s_nop 0
	v_pk_fma_f32 v[20:21], v[44:45], s[18:19], v[22:23] op_sel_hi:[1,0,1]
	s_nop 0
	v_pk_fma_f32 v[18:19], v[46:47], s[18:19], v[20:21] op_sel_hi:[1,0,1]
	s_nop 0
	v_pk_fma_f32 v[16:17], v[48:49], s[18:19], v[18:19] op_sel_hi:[1,0,1]
	s_waitcnt lgkmcnt(0)
	s_barrier
	ds_write_b64 v161, v[16:17]
	s_waitcnt lgkmcnt(0)
	s_barrier
	s_cbranch_scc1 .LBB0_1404
	ds_read2st64_b32 v[230:231], v146 offset1:1
	v_add_u32_e32 v56, 0x1b200, v147
	ds_read_b128 v[50:53], v56
	ds_read_b128 v[218:221], v56 offset:64
	ds_read_b128 v[222:225], v56 offset:128
	ds_read_b128 v[226:229], v56 offset:192
	s_sub_i32 s16, s95, 64
	s_waitcnt lgkmcnt(4)
	v_add_f32_e32 v32, v230, v231
	v_fmamk_f32 v32, v32, 0x3c000000, v211
	v_rsq_f32_e32 v32, v32
	s_nop 0
	v_pk_mul_f32 v[12:13], v[12:13], v[32:33] op_sel_hi:[1,0]
	v_pk_mul_f32 v[8:9], v[8:9], v[32:33] op_sel_hi:[1,0]
	s_waitcnt lgkmcnt(3)
	v_pk_mul_f32 v[12:13], v[50:51], v[12:13]
	v_lshlrev_b32_e32 v50, 16, v142
	v_and_b32_e32 v51, 0xffff0000, v142
	v_pk_mul_f32 v[12:13], v[12:13], v[50:51]
	v_pk_mul_f32 v[4:5], v[4:5], v[32:33] op_sel_hi:[1,0]
	v_cvt_pk_bf16_f32 v50, v12, v13
	v_pk_mul_f32 v[12:13], v[14:15], v[32:33] op_sel_hi:[1,0]
	v_lshlrev_b32_e32 v14, 16, v143
	v_pk_mul_f32 v[12:13], v[52:53], v[12:13]
	v_and_b32_e32 v15, 0xffff0000, v143
	v_pk_mul_f32 v[12:13], v[12:13], v[14:15]
	v_pk_mul_f32 v[0:1], v[0:1], v[32:33] op_sel_hi:[1,0]
	v_cvt_pk_bf16_f32 v51, v12, v13
	s_waitcnt lgkmcnt(2)
	v_pk_mul_f32 v[8:9], v[218:219], v[8:9]
	s_waitcnt vmcnt(26)
	v_lshlrev_b32_e32 v12, 16, v140
	v_and_b32_e32 v13, 0xffff0000, v140
	v_pk_mul_f32 v[8:9], v[8:9], v[12:13]
	s_nop 0
	v_cvt_pk_bf16_f32 v12, v8, v9
	v_pk_mul_f32 v[8:9], v[10:11], v[32:33] op_sel_hi:[1,0]
	v_lshlrev_b32_e32 v10, 16, v141
	v_pk_mul_f32 v[8:9], v[220:221], v[8:9]
	v_and_b32_e32 v11, 0xffff0000, v141
	v_pk_mul_f32 v[8:9], v[8:9], v[10:11]
	s_nop 0
	v_cvt_pk_bf16_f32 v13, v8, v9
	s_waitcnt lgkmcnt(1)
	v_pk_mul_f32 v[4:5], v[222:223], v[4:5]
	s_waitcnt vmcnt(25)
	v_lshlrev_b32_e32 v8, 16, v114
	v_and_b32_e32 v9, 0xffff0000, v114
	v_pk_mul_f32 v[4:5], v[4:5], v[8:9]
	s_nop 0
	v_cvt_pk_bf16_f32 v8, v4, v5
	v_pk_mul_f32 v[4:5], v[6:7], v[32:33] op_sel_hi:[1,0]
	v_lshlrev_b32_e32 v6, 16, v115
	v_pk_mul_f32 v[4:5], v[224:225], v[4:5]
	v_and_b32_e32 v7, 0xffff0000, v115
	v_pk_mul_f32 v[4:5], v[4:5], v[6:7]
	s_nop 0
	v_cvt_pk_bf16_f32 v9, v4, v5
	s_waitcnt lgkmcnt(0)
	v_pk_mul_f32 v[0:1], v[0:1], v[226:227]
	s_waitcnt vmcnt(24)
	v_lshlrev_b32_e32 v4, 16, v100
	v_and_b32_e32 v5, 0xffff0000, v100
	v_pk_mul_f32 v[0:1], v[0:1], v[4:5]
	s_nop 0
	v_cvt_pk_bf16_f32 v10, v0, v1
	v_pk_mul_f32 v[0:1], v[2:3], v[32:33] op_sel_hi:[1,0]
	v_lshlrev_b32_e32 v2, 16, v101
	v_pk_mul_f32 v[0:1], v[0:1], v[228:229]
	v_and_b32_e32 v3, 0xffff0000, v101
	v_pk_mul_f32 v[0:1], v[0:1], v[2:3]
	s_nop 0
	v_cvt_pk_bf16_f32 v11, v0, v1
	v_lshl_add_u64 v[0:1], v[98:99], 0, s[16:17]
	v_lshlrev_b64 v[4:5], 11, v[0:1]
	v_lshl_add_u64 v[4:5], v[104:105], 0, v[4:5]
	s_mov_b32 s16, s95
	v_permlane16_swap_b32_e32 v50, v12
	v_permlane16_swap_b32_e32 v51, v13
	v_permlane16_swap_b32_e32 v8, v10
	v_permlane16_swap_b32_e32 v9, v11
	global_store_dwordx2 v[4:5], v[50:51], off
	global_store_dwordx2 v[4:5], v[12:13], off offset:8
	global_store_dwordx4 v[4:5], v[8:11], off offset:64
